# P1 in-proj GEMM: light pn==12 tiles skip MFMAs and fragment reads for never-stored padded columns
# baseline (speedup 1.0000x reference)
.LBB0_397:
	v_readfirstlane_b32 s98, v182
	s_bfe_u32 s98, s98, 0x20006
	s_cmp_eq_u32 s6, 12
	s_cselect_b32 s99, 1, 0
	s_cmp_lg_u32 s98, 0
	s_cselect_b32 s98, s99, 0
	v_readlane_b32 s56, v244, 0
	v_readlane_b32 s57, v244, 1
	v_readlane_b32 s58, v244, 2
	v_readlane_b32 s59, v244, 3
	v_readlane_b32 s60, v244, 4
	v_readlane_b32 s61, v244, 5
	s_ashr_i32 s25, s24, 31
	v_readlane_b32 s62, v244, 6
	v_readlane_b32 s63, v244, 7
	s_mov_b64 s[56:57], s[60:61]
	s_lshl_b64 s[26:27], s[24:25], 19
	s_mov_b64 s[58:59], s[62:63]
	s_add_u32 s26, s58, s26
	s_addc_u32 s27, s59, s27
	s_and_b64 s[28:29], s[0:1], exec
	s_cselect_b32 s5, s27, s31
	s_cselect_b32 s8, s26, s30
	s_ashr_i32 s19, s18, 31
	s_lshl_b64 s[28:29], s[18:19], 19
	s_add_u32 s28, s33, s28
	s_addc_u32 s29, s38, s29
	s_and_b64 s[36:37], s[0:1], exec
	s_cselect_b32 s19, s29, s35
	s_cselect_b32 s25, s28, s34
	s_add_u32 s30, s30, 0x40080
	s_addc_u32 s31, s31, 0
	s_add_u32 s53, s34, 0x100
	v_mov_b32_e32 v0, 0
	s_addc_u32 s54, s35, 0
	s_mov_b32 s55, -2
	v_mov_b32_e32 v1, v0
	v_mov_b32_e32 v2, v0
	v_mov_b32_e32 v3, v0
	v_mov_b32_e32 v4, v0
	v_mov_b32_e32 v5, v0
	v_mov_b32_e32 v6, v0
	v_mov_b32_e32 v7, v0
	v_mov_b32_e32 v16, v0
	v_mov_b32_e32 v17, v0
	v_mov_b32_e32 v18, v0
	v_mov_b32_e32 v19, v0
	v_mov_b32_e32 v20, v0
	v_mov_b32_e32 v21, v0
	v_mov_b32_e32 v22, v0
	v_mov_b32_e32 v23, v0
	v_mov_b32_e32 v32, v0
	v_mov_b32_e32 v33, v0
	v_mov_b32_e32 v34, v0
	v_mov_b32_e32 v35, v0
	v_mov_b32_e32 v36, v0
	v_mov_b32_e32 v37, v0
	v_mov_b32_e32 v38, v0
	v_mov_b32_e32 v39, v0
	v_mov_b32_e32 v48, v0
	v_mov_b32_e32 v49, v0
	v_mov_b32_e32 v50, v0
	v_mov_b32_e32 v51, v0
	v_mov_b32_e32 v52, v0
	v_mov_b32_e32 v53, v0
	v_mov_b32_e32 v54, v0
	v_mov_b32_e32 v55, v0
	v_mov_b32_e32 v8, v0
	v_mov_b32_e32 v9, v0
	v_mov_b32_e32 v10, v0
	v_mov_b32_e32 v11, v0
	v_mov_b32_e32 v12, v0
	v_mov_b32_e32 v13, v0
	v_mov_b32_e32 v14, v0
	v_mov_b32_e32 v15, v0
	v_mov_b32_e32 v24, v0
	v_mov_b32_e32 v25, v0
	v_mov_b32_e32 v26, v0
	v_mov_b32_e32 v27, v0
	v_mov_b32_e32 v28, v0
	v_mov_b32_e32 v29, v0
	v_mov_b32_e32 v30, v0
	v_mov_b32_e32 v31, v0
	v_mov_b32_e32 v40, v0
	v_mov_b32_e32 v41, v0
	v_mov_b32_e32 v42, v0
	v_mov_b32_e32 v43, v0
	v_mov_b32_e32 v44, v0
	v_mov_b32_e32 v45, v0
	v_mov_b32_e32 v46, v0
	v_mov_b32_e32 v47, v0
	v_mov_b32_e32 v56, v0
	v_mov_b32_e32 v57, v0
	v_mov_b32_e32 v58, v0
	v_mov_b32_e32 v59, v0
	v_mov_b32_e32 v60, v0
	v_mov_b32_e32 v61, v0
	v_mov_b32_e32 v62, v0
	v_mov_b32_e32 v63, v0
	v_mov_b32_e32 v64, v0
	v_mov_b32_e32 v65, v0
	v_mov_b32_e32 v66, v0
	v_mov_b32_e32 v67, v0
	v_mov_b32_e32 v68, v0
	v_mov_b32_e32 v69, v0
	v_mov_b32_e32 v70, v0
	v_mov_b32_e32 v71, v0
	v_mov_b32_e32 v80, v0
	v_mov_b32_e32 v81, v0
	v_mov_b32_e32 v82, v0
	v_mov_b32_e32 v83, v0
	v_mov_b32_e32 v84, v0
	v_mov_b32_e32 v85, v0
	v_mov_b32_e32 v86, v0
	v_mov_b32_e32 v87, v0
	v_mov_b32_e32 v96, v0
	v_mov_b32_e32 v97, v0
	v_mov_b32_e32 v98, v0
	v_mov_b32_e32 v99, v0
	v_mov_b32_e32 v100, v0
	v_mov_b32_e32 v101, v0
	v_mov_b32_e32 v102, v0
	v_mov_b32_e32 v103, v0
	v_mov_b32_e32 v112, v0
	v_mov_b32_e32 v113, v0
	v_mov_b32_e32 v114, v0
	v_mov_b32_e32 v115, v0
	v_mov_b32_e32 v116, v0
	v_mov_b32_e32 v117, v0
	v_mov_b32_e32 v118, v0
	v_mov_b32_e32 v119, v0
	v_mov_b32_e32 v72, v0
	v_mov_b32_e32 v73, v0
	v_mov_b32_e32 v74, v0
	v_mov_b32_e32 v75, v0
	v_mov_b32_e32 v76, v0
	v_mov_b32_e32 v77, v0
	v_mov_b32_e32 v78, v0
	v_mov_b32_e32 v79, v0
	v_mov_b32_e32 v88, v0
	v_mov_b32_e32 v89, v0
	v_mov_b32_e32 v90, v0
	v_mov_b32_e32 v91, v0
	v_mov_b32_e32 v92, v0
	v_mov_b32_e32 v93, v0
	v_mov_b32_e32 v94, v0
	v_mov_b32_e32 v95, v0
	v_mov_b32_e32 v104, v0
	v_mov_b32_e32 v105, v0
	v_mov_b32_e32 v106, v0
	v_mov_b32_e32 v107, v0
	v_mov_b32_e32 v108, v0
	v_mov_b32_e32 v109, v0
	v_mov_b32_e32 v110, v0
	v_mov_b32_e32 v111, v0
	v_mov_b32_e32 v120, v0
	v_mov_b32_e32 v121, v0
	v_mov_b32_e32 v122, v0
	v_mov_b32_e32 v123, v0
	v_mov_b32_e32 v124, v0
	v_mov_b32_e32 v125, v0
	v_mov_b32_e32 v126, v0
	v_mov_b32_e32 v127, v0
.LBB0_398:
	s_cmp_lg_u32 s98, 0
	s_cbranch_scc1 .Lp1l_r0
	ds_read_b128 v[158:161], v154
	ds_read_b128 v[162:165], v154 offset:1024
	ds_read_b128 v[166:169], v154 offset:2048
	ds_read_b128 v[170:173], v154 offset:3072
	ds_read_b128 v[174:177], v155
	ds_read_b128 v[178:181], v155 offset:1024
	ds_read_b128 v[184:187], v155 offset:2048
	ds_read_b128 v[188:191], v155 offset:3072
.Lp1l_r0:
	s_add_u32 s34, s30, 0xfffc0080
	s_addc_u32 s35, s31, -1
	s_cmp_eq_u32 s55, 12
	s_cselect_b32 s37, s5, s35
	s_cselect_b32 s36, s8, s34
	s_cselect_b32 s35, s19, s54
	s_cselect_b32 s34, s25, s53
	v_lshl_add_u64 v[152:153], s[30:31], 0, v[142:143]
	s_add_i32 m0, s7, 0xc000
	s_cmp_lg_u32 s98, 0
	s_cbranch_scc1 .Lp1l_r1
	ds_read_b128 v[192:195], v156
	ds_read_b128 v[196:199], v156 offset:1024
	ds_read_b128 v[200:203], v156 offset:2048
	ds_read_b128 v[204:207], v156 offset:3072
	ds_read_b128 v[208:211], v156 offset:4096
	ds_read_b128 v[212:215], v156 offset:5120
	ds_read_b128 v[216:219], v156 offset:6144
	ds_read_b128 v[220:223], v156 offset:7168
.Lp1l_r1:
	global_load_lds_dwordx4 v[152:153], off
	v_lshl_add_u64 v[152:153], s[30:31], 0, v[146:147]
	s_add_i32 m0, s7, 0xe000
	s_nop 0
	global_load_lds_dwordx4 v[152:153], off
	s_waitcnt vmcnt(8)
	s_waitcnt lgkmcnt(0)
	s_barrier
	s_setprio 1
	s_waitcnt lgkmcnt(0)
	s_cmp_lg_u32 s98, 0
	s_cbranch_scc1 .Lp1l_m0
	v_mfma_f32_16x16x32_bf16 v[124:127], v[158:161], v[192:195], v[124:127]
	v_mfma_f32_16x16x32_bf16 v[120:123], v[166:169], v[192:195], v[120:123]
	v_mfma_f32_16x16x32_bf16 v[108:111], v[158:161], v[200:203], v[108:111]
	v_mfma_f32_16x16x32_bf16 v[104:107], v[166:169], v[200:203], v[104:107]
	v_mfma_f32_16x16x32_bf16 v[92:95], v[158:161], v[208:211], v[92:95]
	v_mfma_f32_16x16x32_bf16 v[88:91], v[166:169], v[208:211], v[88:91]
	v_mfma_f32_16x16x32_bf16 v[76:79], v[158:161], v[216:219], v[76:79]
	v_mfma_f32_16x16x32_bf16 v[72:75], v[166:169], v[216:219], v[72:75]
	v_mfma_f32_16x16x32_bf16 v[124:127], v[162:165], v[196:199], v[124:127]
	v_mfma_f32_16x16x32_bf16 v[120:123], v[170:173], v[196:199], v[120:123]
	v_mfma_f32_16x16x32_bf16 v[108:111], v[162:165], v[204:207], v[108:111]
	v_mfma_f32_16x16x32_bf16 v[104:107], v[170:173], v[204:207], v[104:107]
	v_mfma_f32_16x16x32_bf16 v[92:95], v[162:165], v[212:215], v[92:95]
	v_mfma_f32_16x16x32_bf16 v[88:91], v[170:173], v[212:215], v[88:91]
	v_mfma_f32_16x16x32_bf16 v[76:79], v[162:165], v[220:223], v[76:79]
	v_mfma_f32_16x16x32_bf16 v[72:75], v[170:173], v[220:223], v[72:75]
	s_setprio 0
	s_setprio 1
	s_cmp_lg_u32 s99, 0
	s_cbranch_scc1 .Lp1l_m0
	v_mfma_f32_16x16x32_bf16 v[116:119], v[174:177], v[192:195], v[116:119]
	v_mfma_f32_16x16x32_bf16 v[112:115], v[184:187], v[192:195], v[112:115]
	v_mfma_f32_16x16x32_bf16 v[100:103], v[174:177], v[200:203], v[100:103]
	v_mfma_f32_16x16x32_bf16 v[96:99], v[184:187], v[200:203], v[96:99]
	v_mfma_f32_16x16x32_bf16 v[84:87], v[174:177], v[208:211], v[84:87]
	v_mfma_f32_16x16x32_bf16 v[80:83], v[184:187], v[208:211], v[80:83]
	v_mfma_f32_16x16x32_bf16 v[68:71], v[174:177], v[216:219], v[68:71]
	v_mfma_f32_16x16x32_bf16 v[64:67], v[184:187], v[216:219], v[64:67]
	v_mfma_f32_16x16x32_bf16 v[116:119], v[178:181], v[196:199], v[116:119]
	v_mfma_f32_16x16x32_bf16 v[112:115], v[188:191], v[196:199], v[112:115]
	v_mfma_f32_16x16x32_bf16 v[100:103], v[178:181], v[204:207], v[100:103]
	v_mfma_f32_16x16x32_bf16 v[96:99], v[188:191], v[204:207], v[96:99]
	v_mfma_f32_16x16x32_bf16 v[84:87], v[178:181], v[212:215], v[84:87]
	v_mfma_f32_16x16x32_bf16 v[80:83], v[188:191], v[212:215], v[80:83]
	v_mfma_f32_16x16x32_bf16 v[68:71], v[178:181], v[220:223], v[68:71]
	v_mfma_f32_16x16x32_bf16 v[64:67], v[188:191], v[220:223], v[64:67]
.Lp1l_m0:
	s_setprio 0
	s_barrier
	s_add_i32 s56, s50, s39
	v_lshl_add_u64 v[152:153], s[34:35], 0, v[130:131]
	s_mov_b32 m0, s56
	s_cmp_lg_u32 s98, 0
	s_cbranch_scc1 .Lp1l_r2
	ds_read_b128 v[192:195], v156 offset:16384
	ds_read_b128 v[196:199], v156 offset:17408
	ds_read_b128 v[200:203], v156 offset:18432
	ds_read_b128 v[204:207], v156 offset:19456
	ds_read_b128 v[208:211], v156 offset:20480
	ds_read_b128 v[212:215], v156 offset:21504
	ds_read_b128 v[216:219], v156 offset:22528
	ds_read_b128 v[220:223], v156 offset:23552
.Lp1l_r2:
	global_load_lds_dwordx4 v[152:153], off
	s_add_i32 m0, s56, 0x2000
	s_add_u32 s56, s34, 0x40000
	v_lshl_add_u64 v[224:225], s[34:35], 0, v[134:135]
	s_addc_u32 s57, s35, 0
	s_add_i32 s58, s51, s39
	global_load_lds_dwordx4 v[224:225], off
	v_lshl_add_u64 v[226:227], s[56:57], 0, v[130:131]
	s_mov_b32 m0, s58
	v_lshl_add_u64 v[228:229], s[36:37], 0, v[132:133]
	global_load_lds_dwordx4 v[226:227], off
	v_lshl_add_u64 v[226:227], s[56:57], 0, v[134:135]
	s_add_i32 m0, s58, 0x2000
	s_nop 0
	global_load_lds_dwordx4 v[226:227], off
	v_lshl_add_u64 v[226:227], s[36:37], 0, v[128:129]
	s_mov_b32 m0, s7
	s_nop 0
	global_load_lds_dwordx4 v[226:227], off
	s_mov_b32 m0, s40
	s_nop 0
	global_load_lds_dwordx4 v[228:229], off
	s_waitcnt vmcnt(8)
	s_waitcnt lgkmcnt(0)
	s_barrier
	s_setprio 1
	s_waitcnt lgkmcnt(0)
	s_cmp_lg_u32 s98, 0
	s_cbranch_scc1 .Lp1l_m1
	v_mfma_f32_16x16x32_bf16 v[60:63], v[158:161], v[192:195], v[60:63]
	v_mfma_f32_16x16x32_bf16 v[56:59], v[166:169], v[192:195], v[56:59]
	v_mfma_f32_16x16x32_bf16 v[44:47], v[158:161], v[200:203], v[44:47]
	v_mfma_f32_16x16x32_bf16 v[40:43], v[166:169], v[200:203], v[40:43]
	v_mfma_f32_16x16x32_bf16 v[28:31], v[158:161], v[208:211], v[28:31]
	v_mfma_f32_16x16x32_bf16 v[24:27], v[166:169], v[208:211], v[24:27]
	v_mfma_f32_16x16x32_bf16 v[12:15], v[158:161], v[216:219], v[12:15]
	v_mfma_f32_16x16x32_bf16 v[8:11], v[166:169], v[216:219], v[8:11]
	v_mfma_f32_16x16x32_bf16 v[60:63], v[162:165], v[196:199], v[60:63]
	v_mfma_f32_16x16x32_bf16 v[56:59], v[170:173], v[196:199], v[56:59]
	v_mfma_f32_16x16x32_bf16 v[44:47], v[162:165], v[204:207], v[44:47]
	v_mfma_f32_16x16x32_bf16 v[40:43], v[170:173], v[204:207], v[40:43]
	v_mfma_f32_16x16x32_bf16 v[28:31], v[162:165], v[212:215], v[28:31]
	v_mfma_f32_16x16x32_bf16 v[24:27], v[170:173], v[212:215], v[24:27]
	v_mfma_f32_16x16x32_bf16 v[12:15], v[162:165], v[220:223], v[12:15]
	v_mfma_f32_16x16x32_bf16 v[8:11], v[170:173], v[220:223], v[8:11]
	s_setprio 0
	s_setprio 1
	s_cmp_lg_u32 s99, 0
	s_cbranch_scc1 .Lp1l_m1
	v_mfma_f32_16x16x32_bf16 v[52:55], v[174:177], v[192:195], v[52:55]
	v_mfma_f32_16x16x32_bf16 v[48:51], v[184:187], v[192:195], v[48:51]
	v_mfma_f32_16x16x32_bf16 v[36:39], v[174:177], v[200:203], v[36:39]
	v_mfma_f32_16x16x32_bf16 v[32:35], v[184:187], v[200:203], v[32:35]
	v_mfma_f32_16x16x32_bf16 v[20:23], v[174:177], v[208:211], v[20:23]
	v_mfma_f32_16x16x32_bf16 v[16:19], v[184:187], v[208:211], v[16:19]
	v_mfma_f32_16x16x32_bf16 v[4:7], v[174:177], v[216:219], v[4:7]
	v_mfma_f32_16x16x32_bf16 v[0:3], v[184:187], v[216:219], v[0:3]
	v_mfma_f32_16x16x32_bf16 v[52:55], v[178:181], v[196:199], v[52:55]
	v_mfma_f32_16x16x32_bf16 v[48:51], v[188:191], v[196:199], v[48:51]
	v_mfma_f32_16x16x32_bf16 v[36:39], v[178:181], v[204:207], v[36:39]
	v_mfma_f32_16x16x32_bf16 v[32:35], v[188:191], v[204:207], v[32:35]
	v_mfma_f32_16x16x32_bf16 v[20:23], v[178:181], v[212:215], v[20:23]
	v_mfma_f32_16x16x32_bf16 v[16:19], v[188:191], v[212:215], v[16:19]
	v_mfma_f32_16x16x32_bf16 v[4:7], v[178:181], v[220:223], v[4:7]
	v_mfma_f32_16x16x32_bf16 v[0:3], v[188:191], v[220:223], v[0:3]
.Lp1l_m1:
	s_setprio 0
	s_barrier
	s_add_i32 s56, 0, 0x18000
	v_add_u32_e32 v136, s56, v145
	s_add_i32 s57, 0, 0x1c000
	s_cmp_lg_u32 s98, 0
	s_cbranch_scc1 .Lp1l_r3
	ds_read_b128 v[158:161], v136
	ds_read_b128 v[162:165], v136 offset:1024
	ds_read_b128 v[166:169], v136 offset:2048
	ds_read_b128 v[170:173], v136 offset:3072
	v_add_u32_e32 v136, s57, v145
	ds_read_b128 v[174:177], v136
	ds_read_b128 v[178:181], v136 offset:1024
	ds_read_b128 v[184:187], v136 offset:2048
	ds_read_b128 v[188:191], v136 offset:3072
.Lp1l_r3:
	s_add_u32 s36, s36, 0x40000
	s_addc_u32 s37, s37, 0
	s_mov_b32 m0, s41
	v_lshl_add_u64 v[230:231], s[36:37], 0, v[128:129]
	s_cmp_lg_u32 s98, 0
	s_cbranch_scc1 .Lp1l_r4
	ds_read_b128 v[192:195], v156 offset:32768
	ds_read_b128 v[196:199], v156 offset:33792
	ds_read_b128 v[200:203], v156 offset:34816
	ds_read_b128 v[204:207], v156 offset:35840
	ds_read_b128 v[208:211], v156 offset:36864
	ds_read_b128 v[212:215], v156 offset:37888
	ds_read_b128 v[216:219], v156 offset:38912
	ds_read_b128 v[220:223], v156 offset:39936
.Lp1l_r4:
	global_load_lds_dwordx4 v[230:231], off
	v_lshl_add_u64 v[230:231], s[36:37], 0, v[132:133]
	s_mov_b32 m0, s42
	s_nop 0
	global_load_lds_dwordx4 v[230:231], off
	s_waitcnt vmcnt(8)
	s_waitcnt lgkmcnt(0)
	s_barrier
	s_setprio 1
	s_waitcnt lgkmcnt(0)
	s_cmp_lg_u32 s98, 0
	s_cbranch_scc1 .Lp1l_m2
	v_mfma_f32_16x16x32_bf16 v[124:127], v[158:161], v[192:195], v[124:127]
	v_mfma_f32_16x16x32_bf16 v[120:123], v[166:169], v[192:195], v[120:123]
	v_mfma_f32_16x16x32_bf16 v[108:111], v[158:161], v[200:203], v[108:111]
	v_mfma_f32_16x16x32_bf16 v[104:107], v[166:169], v[200:203], v[104:107]
	v_mfma_f32_16x16x32_bf16 v[92:95], v[158:161], v[208:211], v[92:95]
	v_mfma_f32_16x16x32_bf16 v[88:91], v[166:169], v[208:211], v[88:91]
	v_mfma_f32_16x16x32_bf16 v[76:79], v[158:161], v[216:219], v[76:79]
	v_mfma_f32_16x16x32_bf16 v[72:75], v[166:169], v[216:219], v[72:75]
	v_mfma_f32_16x16x32_bf16 v[124:127], v[162:165], v[196:199], v[124:127]
	v_mfma_f32_16x16x32_bf16 v[120:123], v[170:173], v[196:199], v[120:123]
	v_mfma_f32_16x16x32_bf16 v[108:111], v[162:165], v[204:207], v[108:111]
	v_mfma_f32_16x16x32_bf16 v[104:107], v[170:173], v[204:207], v[104:107]
	v_mfma_f32_16x16x32_bf16 v[92:95], v[162:165], v[212:215], v[92:95]
	v_mfma_f32_16x16x32_bf16 v[88:91], v[170:173], v[212:215], v[88:91]
	v_mfma_f32_16x16x32_bf16 v[76:79], v[162:165], v[220:223], v[76:79]
	v_mfma_f32_16x16x32_bf16 v[72:75], v[170:173], v[220:223], v[72:75]
	s_setprio 0
	s_setprio 1
	s_cmp_lg_u32 s99, 0
	s_cbranch_scc1 .Lp1l_m2
	v_mfma_f32_16x16x32_bf16 v[116:119], v[174:177], v[192:195], v[116:119]
	v_mfma_f32_16x16x32_bf16 v[112:115], v[184:187], v[192:195], v[112:115]
	v_mfma_f32_16x16x32_bf16 v[100:103], v[174:177], v[200:203], v[100:103]
	v_mfma_f32_16x16x32_bf16 v[96:99], v[184:187], v[200:203], v[96:99]
	v_mfma_f32_16x16x32_bf16 v[84:87], v[174:177], v[208:211], v[84:87]
	v_mfma_f32_16x16x32_bf16 v[80:83], v[184:187], v[208:211], v[80:83]
	v_mfma_f32_16x16x32_bf16 v[68:71], v[174:177], v[216:219], v[68:71]
	v_mfma_f32_16x16x32_bf16 v[64:67], v[184:187], v[216:219], v[64:67]
	v_mfma_f32_16x16x32_bf16 v[116:119], v[178:181], v[196:199], v[116:119]
	v_mfma_f32_16x16x32_bf16 v[112:115], v[188:191], v[196:199], v[112:115]
	v_mfma_f32_16x16x32_bf16 v[100:103], v[178:181], v[204:207], v[100:103]
	v_mfma_f32_16x16x32_bf16 v[96:99], v[188:191], v[204:207], v[96:99]
	v_mfma_f32_16x16x32_bf16 v[84:87], v[178:181], v[212:215], v[84:87]
	v_mfma_f32_16x16x32_bf16 v[80:83], v[188:191], v[212:215], v[80:83]
	v_mfma_f32_16x16x32_bf16 v[68:71], v[178:181], v[220:223], v[68:71]
	v_mfma_f32_16x16x32_bf16 v[64:67], v[188:191], v[220:223], v[64:67]
.Lp1l_m2:
	s_setprio 0
	s_barrier
	s_add_i32 s36, s56, s39
	v_lshl_add_u64 v[152:153], v[152:153], 0, s[12:13]
	s_mov_b32 m0, s36
	s_cmp_lg_u32 s98, 0
	s_cbranch_scc1 .Lp1l_r5
	ds_read_b128 v[192:195], v156 offset:49152
	ds_read_b128 v[196:199], v156 offset:50176
	ds_read_b128 v[200:203], v156 offset:51200
	ds_read_b128 v[204:207], v156 offset:52224
	ds_read_b128 v[208:211], v156 offset:53248
	ds_read_b128 v[212:215], v156 offset:54272
	ds_read_b128 v[216:219], v156 offset:55296
	ds_read_b128 v[220:223], v156 offset:56320
.Lp1l_r5:
	global_load_lds_dwordx4 v[152:153], off
	s_add_i32 m0, s36, 0x2000
	s_add_u32 s34, s34, 0x40080
	v_lshl_add_u64 v[152:153], v[224:225], 0, s[12:13]
	s_addc_u32 s35, s35, 0
	s_add_i32 s36, s57, s39
	global_load_lds_dwordx4 v[152:153], off
	v_lshl_add_u64 v[152:153], s[34:35], 0, v[130:131]
	s_mov_b32 m0, s36
	s_nop 0
	global_load_lds_dwordx4 v[152:153], off
	v_lshl_add_u64 v[152:153], s[34:35], 0, v[134:135]
	s_add_i32 m0, s36, 0x2000
	s_nop 0
	global_load_lds_dwordx4 v[152:153], off
	v_lshl_add_u64 v[152:153], v[226:227], 0, s[12:13]
	s_mov_b32 m0, s45
	s_nop 0
	global_load_lds_dwordx4 v[152:153], off
	v_lshl_add_u64 v[152:153], v[228:229], 0, s[12:13]
	s_mov_b32 m0, s46
	s_nop 0
	global_load_lds_dwordx4 v[152:153], off
	s_waitcnt vmcnt(8)
	s_waitcnt lgkmcnt(0)
	s_barrier
	s_setprio 1
	s_waitcnt lgkmcnt(0)
	s_cmp_lg_u32 s98, 0
	s_cbranch_scc1 .Lp1l_m3
	v_mfma_f32_16x16x32_bf16 v[60:63], v[158:161], v[192:195], v[60:63]
	v_mfma_f32_16x16x32_bf16 v[56:59], v[166:169], v[192:195], v[56:59]
	v_mfma_f32_16x16x32_bf16 v[44:47], v[158:161], v[200:203], v[44:47]
	v_mfma_f32_16x16x32_bf16 v[40:43], v[166:169], v[200:203], v[40:43]
	v_mfma_f32_16x16x32_bf16 v[28:31], v[158:161], v[208:211], v[28:31]
	v_mfma_f32_16x16x32_bf16 v[24:27], v[166:169], v[208:211], v[24:27]
	v_mfma_f32_16x16x32_bf16 v[12:15], v[158:161], v[216:219], v[12:15]
	v_mfma_f32_16x16x32_bf16 v[8:11], v[166:169], v[216:219], v[8:11]
	v_mfma_f32_16x16x32_bf16 v[60:63], v[162:165], v[196:199], v[60:63]
	v_mfma_f32_16x16x32_bf16 v[56:59], v[170:173], v[196:199], v[56:59]
	v_mfma_f32_16x16x32_bf16 v[44:47], v[162:165], v[204:207], v[44:47]
	v_mfma_f32_16x16x32_bf16 v[40:43], v[170:173], v[204:207], v[40:43]
	v_mfma_f32_16x16x32_bf16 v[28:31], v[162:165], v[212:215], v[28:31]
	v_mfma_f32_16x16x32_bf16 v[24:27], v[170:173], v[212:215], v[24:27]
	v_mfma_f32_16x16x32_bf16 v[12:15], v[162:165], v[220:223], v[12:15]
	v_mfma_f32_16x16x32_bf16 v[8:11], v[170:173], v[220:223], v[8:11]
	s_setprio 0
	s_setprio 1
	s_cmp_lg_u32 s99, 0
	s_cbranch_scc1 .Lp1l_m3
	v_mfma_f32_16x16x32_bf16 v[52:55], v[174:177], v[192:195], v[52:55]
	v_mfma_f32_16x16x32_bf16 v[48:51], v[184:187], v[192:195], v[48:51]
	v_mfma_f32_16x16x32_bf16 v[36:39], v[174:177], v[200:203], v[36:39]
	v_mfma_f32_16x16x32_bf16 v[32:35], v[184:187], v[200:203], v[32:35]
	v_mfma_f32_16x16x32_bf16 v[20:23], v[174:177], v[208:211], v[20:23]
	v_mfma_f32_16x16x32_bf16 v[16:19], v[184:187], v[208:211], v[16:19]
	v_mfma_f32_16x16x32_bf16 v[4:7], v[174:177], v[216:219], v[4:7]
	v_mfma_f32_16x16x32_bf16 v[0:3], v[184:187], v[216:219], v[0:3]
	v_mfma_f32_16x16x32_bf16 v[52:55], v[178:181], v[196:199], v[52:55]
	v_mfma_f32_16x16x32_bf16 v[48:51], v[188:191], v[196:199], v[48:51]
	v_mfma_f32_16x16x32_bf16 v[36:39], v[178:181], v[204:207], v[36:39]
	v_mfma_f32_16x16x32_bf16 v[32:35], v[188:191], v[204:207], v[32:35]
	v_mfma_f32_16x16x32_bf16 v[20:23], v[178:181], v[212:215], v[20:23]
	v_mfma_f32_16x16x32_bf16 v[16:19], v[188:191], v[212:215], v[16:19]
	v_mfma_f32_16x16x32_bf16 v[4:7], v[178:181], v[220:223], v[4:7]
	v_mfma_f32_16x16x32_bf16 v[0:3], v[188:191], v[220:223], v[0:3]
.Lp1l_m3:
	s_setprio 0
	s_barrier
	s_add_i32 s55, s55, 2
	s_add_u32 s30, s30, 0x100
	s_addc_u32 s31, s31, 0
	s_add_u32 s53, s53, 0x100
	s_addc_u32 s54, s54, 0
	s_cmp_gt_u32 s55, 13
	s_cbranch_scc0 .LBB0_398
	s_and_b64 vcc, exec, s[14:15]
	s_cbranch_vccz .LBB0_401
	s_barrier
